# conv phase: the SSD conv-bias pointer is read from the kernarg segment once instead of before each of the 8 bias loads
# baseline (speedup 1.0000x reference)
; __device__ __forceinline__ const float* pin(int i) { return kargs()->in[i]; }
; __device__ __forceinline__ void phase_conv(const Params& p, int l, const XcdBarrier& xbar) {
;     ...
;     for (int e = 0; e < 8; ++e) bias[e] = ssd ? pin(17)[l * 768 + ch + e] : 0.f;
.LBB0_436:
	s_or_b64 exec, exec, s[6:7]
	s_and_saveexec_b64 s[6:7], s[42:43]
	s_cbranch_execz .LBB0_438
	v_lshl_add_u64 v[14:15], v[12:13], 2, s[2:3]
	global_load_dword v147, v[14:15], off offset:4
.LBB0_438:
	s_or_b64 exec, exec, s[6:7]
	v_mov_b32_e32 v145, 0
	v_mov_b32_e32 v144, 0
	s_and_saveexec_b64 s[6:7], s[42:43]
	s_cbranch_execz .LBB0_440
	v_lshl_add_u64 v[14:15], v[12:13], 2, s[2:3]
	global_load_dword v144, v[14:15], off offset:8
.LBB0_440:
	s_or_b64 exec, exec, s[6:7]
	s_and_saveexec_b64 s[6:7], s[42:43]
	s_cbranch_execz .LBB0_442
	v_lshl_add_u64 v[14:15], v[12:13], 2, s[2:3]
	global_load_dword v145, v[14:15], off offset:12
.LBB0_442:
	s_or_b64 exec, exec, s[6:7]
	v_mov_b32_e32 v143, 0
	v_mov_b32_e32 v142, 0
	s_and_saveexec_b64 s[6:7], s[42:43]
	s_cbranch_execz .LBB0_444
	v_lshl_add_u64 v[14:15], v[12:13], 2, s[2:3]
	global_load_dword v142, v[14:15], off offset:16
.LBB0_444:
	s_or_b64 exec, exec, s[6:7]
	s_and_saveexec_b64 s[6:7], s[42:43]
	s_cbranch_execz .LBB0_446
	v_lshl_add_u64 v[14:15], v[12:13], 2, s[2:3]
	global_load_dword v143, v[14:15], off offset:20
.LBB0_446:
	s_or_b64 exec, exec, s[6:7]
	v_mov_b32_e32 v141, 0
	v_mov_b32_e32 v140, 0
	s_and_saveexec_b64 s[6:7], s[42:43]
	s_cbranch_execz .LBB0_448
	v_lshl_add_u64 v[14:15], v[12:13], 2, s[2:3]
	global_load_dword v140, v[14:15], off offset:24
.LBB0_448:
	s_or_b64 exec, exec, s[6:7]
	s_and_saveexec_b64 s[6:7], s[42:43]
	s_cbranch_execz .LBB0_450
	v_lshl_add_u64 v[12:13], v[12:13], 2, s[2:3]
	global_load_dword v141, v[12:13], off offset:28
